# compressed-attention block selection: top-16 of the 64 block scores by a 32-step radix select on order-preserving integer keys (lower index wins ties) instead of 64 readlane/compare rounds per token
# speedup vs baseline: 1.0048x; 1.0048x over previous
; DI void cmp_attn_item(const Params& P, int it, u16* sQ, u16* sK, u16* sVt, float* sImp) {
;     ...
;   for (int q = 0; q < 4; ++q) {
;     const int tok = 4 * w + q, t = t0 + tok;
;     float v = sImp[(0 * 16 + tok) * 64 + lane] + sImp[(1 * 16 + tok) * 64 + lane] + sImp[(2 * 16 + tok) * 64 + lane] + sImp[(3 * 16 + tok) * 64 + lane];
;     const int cur = t >> 6;
;     if (lane == 0 || lane == cur) v = 1e9f;
;     else if (lane * 64 > t) v = -1e30f;
;     int cnt = 0;
; #pragma unroll
;     for (int i2 = 0; i2 < 64; ++i2) {
;       float vi = __builtin_bit_cast(float, __builtin_amdgcn_readlane(__builtin_bit_cast(int, v), i2));
;       cnt += (vi > v || (vi == v && i2 < lane)) ? 1 : 0;
;     }
;     u64 mask = __ballot(cnt < 16);
;     if (lane == 0) SEL[tb + t] = mask;
;   }
.LBB0_214:
	v_add_u32_e32 v5, s46, v1
	ds_read2st64_b32 v[6:7], v5 offset1:16
	v_readlane_b32 s40, v245, 16
	v_readlane_b32 s41, v245, 17
	s_waitcnt lgkmcnt(0)
	v_add_f32_e32 v8, v6, v7
	ds_read2st64_b32 v[6:7], v5 offset0:32 offset1:48
	s_waitcnt lgkmcnt(0)
	v_add_f32_e32 v5, v8, v6
	v_ashrrev_i32_e32 v6, 6, v0
	v_cmp_eq_u32_e32 vcc, v46, v6
	v_add_f32_e32 v5, v5, v7
	s_or_b64 s[2:3], s[36:37], vcc
	v_cmp_le_i32_e32 vcc, v4, v0
	s_nop 1
	v_cndmask_b32_e32 v5, v186, v5, vcc
	v_cndmask_b32_e64 v5, v5, v189, s[2:3]
	v_ashrrev_i32_e32 v6, 31, v5
	v_or_b32_e32 v6, 0x80000000, v6
	v_xor_b32_e32 v6, v6, v5
	s_mov_b32 s40, 0
	s_brev_b32 s41, 1
.Ltopk_bit:
	s_or_b32 s2, s40, s41
	v_cmp_le_u32_e32 vcc, s2, v6
	s_bcnt1_i32_b64 s3, vcc
	s_cmp_ge_u32 s3, 16
	s_cselect_b32 s40, s2, s40
	s_lshr_b32 s41, s41, 1
	s_cmp_lg_u32 s41, 0
	s_cbranch_scc1 .Ltopk_bit
	v_cmp_eq_u32_e64 s[2:3], s40, v6
	v_cmp_lt_u32_e32 vcc, s40, v6
	s_bcnt1_i32_b64 s40, vcc
	s_sub_i32 s40, 16, s40
	s_nop 0
	v_mbcnt_lo_u32_b32 v7, s2, 0
	v_mbcnt_hi_u32_b32 v7, s3, v7
	v_cmp_gt_u32_e64 s[40:41], s40, v7
	s_and_b64 s[2:3], s[2:3], s[40:41]
	s_or_b64 vcc, vcc, s[2:3]
	s_and_saveexec_b64 s[2:3], s[36:37]
	s_cbranch_execz .LBB0_213
	v_mov_b64_e32 v[6:7], vcc
	global_store_dwordx2 v[2:3], v[6:7], off
	s_branch .LBB0_213
